# hardware transposed LDS reads (ds_read_b64_tr_b16): V tile of attention and K/V tiles of the kv-state phase stored row-major with wide writes; unrolled attention path for full tiles
# speedup vs baseline: 1.1638x; 1.0071x over previous
.LBB0_83:
	v_and_b32_e32 v1, 63, v0
	v_lshlrev_b32_e32 v1, 2, v1
	s_lshl_b32 s2, s3, 2
	v_mov_b32_e32 v2, s2
	s_waitcnt lgkmcnt(0)
	v_lshrrev_b32_e32 v7, 1, v0
	v_and_b32_e32 v21, 31, v0
	v_bfe_u32 v8, v0, 5, 1
	v_lshlrev_b32_e32 v131, 2, v8
	s_waitcnt lgkmcnt(0)
	s_lshl_b32 s4, s65, 7
	s_movk_i32 s5, 0x60
	s_or_b32 s4, s1, s4
	v_and_or_b32 v132, v7, s5, v21
	v_or_b32_e32 v126, s4, v132
	v_readlane_b32 s4, v254, 4
	v_mov_b64_e32 v[2:3], s[66:67]
	s_lshl_b32 s68, s3, 7
	v_or_b32_e32 v134, s4, v131
	s_movk_i32 s4, 0xc00
	v_mad_i64_i32 v[2:3], s[4:5], v126, s4, v[2:3]
	v_lshlrev_b32_e32 v160, 4, v8
	v_lshl_add_u64 v[2:3], v[2:3], 0, s[68:69]
	v_lshl_add_u64 v[2:3], v[2:3], 0, v[160:161]
	global_load_dwordx4 v[110:113], v[2:3], off
	global_load_dwordx4 v[114:117], v[2:3], off offset:32
	global_load_dwordx4 v[118:121], v[2:3], off offset:64
	global_load_dwordx4 v[122:125], v[2:3], off offset:96
	v_xor_b32_e32 v133, 0x80, v1
	v_lshlrev_b64 v[16:17], 1, v[16:17]
	v_mul_u32_u24_e32 v23, 0x84, v21
	v_lshl_add_u64 v[16:17], s[66:67], 0, v[16:17]
	v_mov_b32_e32 v0, v161
	v_lshlrev_b32_e32 v22, 3, v8
	v_lshl_add_u64 v[128:129], v[18:19], 1, v[16:17]
	v_lshlrev_b32_e32 v16, 1, v23
	v_readlane_b32 s4, v254, 60
	s_lshl_b32 s50, s6, 8
	v_mul_u32_u24_e32 v153, 0x2100, v20
	v_and_b32_e32 v22, 15, v21
	v_lshrrev_b32_e32 v22, 2, v22
	v_bfe_u32 v23, v22, 1, 1
	v_lshl_add_u32 v22, v8, 2, v22
	v_lshlrev_b32_e32 v22, 7, v22
	v_lshl_add_u32 v22, v23, 6, v22
	v_bfe_u32 v16, v21, 4, 1
	v_lshlrev_b32_e32 v16, 5, v16
	v_and_b32_e32 v23, 3, v21
	v_lshl_add_u32 v16, v23, 3, v16
	v_add3_u32 v154, v22, v16, s4
	v_mul_u32_u24_e32 v16, 0x90, v21
	v_add3_u32 v156, v16, v160, s33
	v_lshlrev_b32_e32 v157, 1, v18
	s_lshl_b32 s2, s3, 6
	s_mov_b32 s3, 0
	s_addk_i32 s50, 0x3f00
	v_ashrrev_i32_e32 v127, 31, v126
	s_movk_i32 s68, 0xc00
	v_or_b32_e32 v135, 1, v134
	v_or_b32_e32 v136, 2, v134
	v_or_b32_e32 v137, 3, v134
	v_or_b32_e32 v139, 8, v134
	v_or_b32_e32 v140, 9, v134
	v_or_b32_e32 v142, 10, v134
	v_or_b32_e32 v143, 11, v134
	v_or_b32_e32 v144, 16, v134
	v_or_b32_e32 v145, 17, v134
	v_or_b32_e32 v146, 18, v134
	v_or_b32_e32 v147, 19, v134
	v_or_b32_e32 v148, 24, v134
	v_or_b32_e32 v149, 25, v134
	v_or_b32_e32 v150, 26, v134
	v_or_b32_e32 v151, 27, v134
	v_mul_u32_u24_e32 v152, 0x90, v130
	s_waitcnt vmcnt(0)
	v_mov_b32_e32 v4, v198
	v_mov_b32_e32 v5, v199
	v_mov_b32_e32 v6, v200
	v_and_b32_e32 v1, 0x7fffffff, v4
	v_and_b32_e32 v2, 0x7fffffff, v5
	s_nop 0
	v_mov_b32_dpp v1, v1 quad_perm:[1,0,3,2] row_mask:0xf bank_mask:0xf bound_ctrl:1
	v_max_f32_e64 v3, |v4|, |v4|
	v_mov_b32_dpp v2, v2 quad_perm:[1,0,3,2] row_mask:0xf bank_mask:0xf bound_ctrl:1
	v_max_f32_e32 v1, v1, v1
	v_max_f32_e64 v4, |v5|, |v5|
	v_max_f32_e32 v2, v2, v2
	v_max_f32_e32 v1, v3, v1
	v_max_f32_e32 v2, v4, v2
	v_mul_f32_e32 v138, 0x3fb8aa3b, v6
	v_mov_b32_dpp v3, v1 quad_perm:[2,3,0,1] row_mask:0xf bank_mask:0xf bound_ctrl:1
	v_mov_b32_dpp v4, v2 quad_perm:[2,3,0,1] row_mask:0xf bank_mask:0xf bound_ctrl:1
	v_max_f32_e32 v3, v3, v3
	v_max_f32_e32 v4, v4, v4
	v_max_f32_e32 v1, v1, v3
	v_max_f32_e32 v2, v2, v4
	s_nop 0
	v_mov_b32_dpp v3, v1 row_half_mirror row_mask:0xf bank_mask:0xf bound_ctrl:1
	v_mov_b32_dpp v4, v2 row_half_mirror row_mask:0xf bank_mask:0xf bound_ctrl:1
	v_max_f32_e32 v3, v3, v3
	v_max_f32_e32 v4, v4, v4
	v_max_f32_e32 v1, v1, v3
	v_max_f32_e32 v2, v2, v4
	s_nop 0
	v_mov_b32_dpp v3, v1 row_mirror row_mask:0xf bank_mask:0xf bound_ctrl:1
	v_mov_b32_dpp v4, v2 row_mirror row_mask:0xf bank_mask:0xf bound_ctrl:1
	v_max_f32_e32 v3, v3, v3
	v_max_f32_e32 v4, v4, v4
	v_max_f32_e32 v1, v1, v3
	v_max_f32_e32 v2, v2, v4
	ds_swizzle_b32 v3, v1 offset:swizzle(SWAP,16)
	ds_swizzle_b32 v4, v2 offset:swizzle(SWAP,16)
	s_waitcnt lgkmcnt(1)
	v_max_f32_e32 v3, v3, v3
	s_waitcnt lgkmcnt(0)
	v_max_f32_e32 v4, v4, v4
	v_max_f32_e32 v1, v1, v3
	v_max_f32_e32 v2, v2, v4
	ds_bpermute_b32 v3, v133, v1
	ds_bpermute_b32 v4, v133, v2
	s_waitcnt lgkmcnt(1)
	v_max_f32_e32 v3, v3, v3
	s_waitcnt lgkmcnt(0)
	v_max_f32_e32 v4, v4, v4
	v_max_f32_e32 v1, v1, v3
	v_max_f32_e32 v2, v2, v4
	v_mul_f32_e32 v1, 0x4138aa3b, v1
	v_mul_f32_e32 v1, v1, v2
	v_max_f32_e32 v141, v1, v138
	v_xor_b32_e32 v32, 0x80000000, v141
	s_nop 0
	v_mov_b32_e32 v14, v0
	v_mov_b32_e32 v15, v0
	v_mov_b32_e32 v1, v0
	v_mov_b32_e32 v2, v0
	v_mov_b32_e32 v3, v0
	v_mov_b32_e32 v4, v0
	v_mov_b32_e32 v5, v0
	v_mov_b32_e32 v6, v0
	v_mov_b32_e32 v7, v0
	v_mov_b32_e32 v8, v0
	v_mov_b32_e32 v9, v0
	v_mov_b32_e32 v10, v0
	v_mov_b32_e32 v11, v0
	v_mov_b32_e32 v12, v0
	v_mov_b32_e32 v13, v0
	v_mov_b64_e32 v[30:31], v[14:15]
	v_mov_b32_e32 v33, v32
	v_mov_b32_e32 v34, v32
	v_mov_b32_e32 v35, v32
	v_mov_b32_e32 v36, v32
	v_mov_b32_e32 v37, v32
	v_mov_b32_e32 v38, v32
	v_mov_b32_e32 v39, v32
	v_mov_b32_e32 v40, v32
	v_mov_b32_e32 v41, v32
	v_mov_b32_e32 v42, v32
	v_mov_b32_e32 v43, v32
	v_mov_b32_e32 v44, v32
	v_mov_b32_e32 v45, v32
	v_mov_b32_e32 v46, v32
	v_mov_b32_e32 v47, v32
	v_mov_b64_e32 v[28:29], v[12:13]
	v_mov_b64_e32 v[26:27], v[10:11]
	v_mov_b64_e32 v[24:25], v[8:9]
	v_mov_b64_e32 v[22:23], v[6:7]
	v_mov_b64_e32 v[20:21], v[4:5]
	v_mov_b64_e32 v[18:19], v[2:3]
	v_mov_b64_e32 v[16:17], v[0:1]
	v_mov_b32_e32 v155, v0
	s_branch .LBB0_86

.LBB0_86:
	s_cmp_gt_u32 s3, 2
	s_cselect_b64 s[4:5], -1, 0
	s_add_i32 s6, s3, s0
	s_cmp_lt_u32 s6, 64
	s_cselect_b64 s[6:7], -1, 0
	s_or_b64 s[6:7], s[4:5], s[6:7]
	v_cndmask_b32_e64 v48, 0, 1, s[6:7]
	s_bitcmp1_b32 s3, 0
	s_cselect_b32 s42, 0x4400, 0
	v_cmp_ne_u32_e64 s[4:5], 1, v48
	s_andn2_b64 vcc, exec, s[6:7]
	s_cbranch_vccnz .LBB0_88
	s_lshl_b32 s6, s42, 1
	s_add_i32 s6, s33, s6
	v_add3_u32 v48, s6, v152, v157
	s_waitcnt vmcnt(4)
	ds_write_b128 v48, v[90:93]
	ds_write_b128 v48, v[86:89] offset:16
	ds_write_b128 v48, v[82:85] offset:32
	ds_write_b128 v48, v[78:81] offset:48
	v_lshlrev_b32_e32 v49, 7, v130
	v_bfe_u32 v50, v130, 1, 1
	v_lshlrev_b32_e32 v50, 6, v50
	v_xor_b32_e32 v50, v50, v157
	v_add3_u32 v48, s6, v49, v50
	s_waitcnt vmcnt(3)
	ds_write_b128 v48, v[94:97] offset:18432
	s_waitcnt vmcnt(2)
	ds_write_b128 v48, v[98:101] offset:18448
	s_waitcnt vmcnt(1)
	ds_write_b128 v48, v[102:105] offset:18464
	s_waitcnt vmcnt(0)
	ds_write_b128 v48, v[106:109] offset:18480

.LBB0_95:
	s_or_b64 vcc, s[4:5], s[92:93]
	s_cbranch_vccz .Lat_full
	s_mov_b32 s42, 3
	s_mov_b32 s43, -1
	s_and_b64 vcc, exec, s[4:5]
	s_cbranch_vccz .Lat_lo
	s_mov_b32 s51, s49

.Lat_dg:
	s_mul_i32 s32, s51, 0x1200
	v_add_u32_e32 v159, s32, v159
	s_lshl_b32 s32, s51, 12
	v_add_u32_e32 v158, s32, v158
	v_xor_b32_e32 v172, 64, v158
	ds_read_b128 v[204:207], v159
	ds_read_b128 v[208:211], v159 offset:32
	ds_read_b128 v[212:215], v159 offset:64
	ds_read_b128 v[232:235], v159 offset:96
	s_waitcnt lgkmcnt(3)
	v_mfma_f32_32x32x16_bf16 v[62:77], v[204:207], v[110:113], v[32:47]
	s_waitcnt lgkmcnt(2)
	v_mfma_f32_32x32x16_bf16 v[62:77], v[208:211], v[114:117], v[62:77]
	s_waitcnt lgkmcnt(1)
	v_mfma_f32_32x32x16_bf16 v[62:77], v[212:215], v[118:121], v[62:77]
	s_waitcnt lgkmcnt(0)
	v_mfma_f32_32x32x16_bf16 v[62:77], v[232:235], v[122:125], v[62:77]
	s_cmp_lt_u32 s51, s42
	s_cbranch_scc0 .Lat_p_nok
	ds_read_b128 v[204:207], v159 offset:4608
	ds_read_b128 v[208:211], v159 offset:4640
	ds_read_b128 v[212:215], v159 offset:4672
	ds_read_b128 v[232:235], v159 offset:4704

.Lat_mid:
	ds_read_b64_tr_b16 v[236:237], v158
	ds_read_b64_tr_b16 v[238:239], v158 offset:1024
	ds_read_b64_tr_b16 v[240:241], v158 offset:2048
	ds_read_b64_tr_b16 v[242:243], v158 offset:3072
	ds_read_b64_tr_b16 v[164:165], v172
	ds_read_b64_tr_b16 v[166:167], v172 offset:1024
	ds_read_b64_tr_b16 v[168:169], v172 offset:2048
	ds_read_b64_tr_b16 v[170:171], v172 offset:3072
	s_cmp_eq_u32 s51, s43
	s_cbranch_scc0 .Lat_nomask
	v_cndmask_b32_e64 v48, 0, v48, s[6:7]
	v_cndmask_b32_e64 v49, 0, v49, s[8:9]
	v_cndmask_b32_e64 v50, 0, v50, s[10:11]
	v_cndmask_b32_e64 v51, 0, v51, s[12:13]
	v_cndmask_b32_e64 v52, 0, v52, s[14:15]
	v_cndmask_b32_e64 v53, 0, v53, s[16:17]
	v_cndmask_b32_e64 v54, 0, v54, s[18:19]
	v_cndmask_b32_e64 v55, 0, v55, s[20:21]
	v_cndmask_b32_e64 v56, 0, v56, s[22:23]
	v_cndmask_b32_e64 v57, 0, v57, s[24:25]
	v_cndmask_b32_e64 v58, 0, v58, s[26:27]
	v_cndmask_b32_e64 v59, 0, v59, s[28:29]
	v_cndmask_b32_e64 v60, 0, v60, s[30:31]
	v_cndmask_b32_e64 v61, 0, v61, s[34:35]
	v_cndmask_b32_e64 v216, 0, v216, s[36:37]
	v_cndmask_b32_e64 v217, 0, v217, s[38:39]
.Lat_nomask:
	s_cmp_lt_u32 s51, s42
	s_cbranch_scc0 .Lat_last
	s_waitcnt lgkmcnt(11)
	v_mfma_f32_32x32x16_bf16 v[62:77], v[204:207], v[110:113], v[32:47]
	v_pk_add_f32 v[218:219], v[48:49], v[50:51]
	v_pk_add_f32 v[244:245], v[52:53], v[54:55]
	v_pk_add_f32 v[198:199], v[56:57], v[58:59]
	v_pk_add_f32 v[200:201], v[60:61], v[216:217]
	s_waitcnt lgkmcnt(10)
	v_mfma_f32_32x32x16_bf16 v[62:77], v[208:211], v[114:117], v[62:77]
	v_cvt_pk_bf16_f32 v220, v48, v49
	v_cvt_pk_bf16_f32 v221, v50, v51
	v_cvt_pk_bf16_f32 v222, v52, v53
	v_cvt_pk_bf16_f32 v223, v54, v55
	v_pk_add_f32 v[218:219], v[218:219], v[244:245]
	v_pk_add_f32 v[198:199], v[198:199], v[200:201]
	s_waitcnt lgkmcnt(9)
	v_mfma_f32_32x32x16_bf16 v[62:77], v[212:215], v[118:121], v[62:77]
	v_cvt_pk_bf16_f32 v224, v56, v57
	v_cvt_pk_bf16_f32 v225, v58, v59
	v_cvt_pk_bf16_f32 v226, v60, v61
	v_cvt_pk_bf16_f32 v227, v216, v217
	v_pk_add_f32 v[218:219], v[218:219], v[198:199]
	s_waitcnt lgkmcnt(8)
	v_mfma_f32_32x32x16_bf16 v[62:77], v[232:235], v[122:125], v[62:77]
	v_add_f32_e32 v218, v218, v219
	v_add_f32_e32 v155, v155, v218
	s_add_i32 s51, s51, 1
	v_add_u32_e32 v158, 0x1000, v158
	v_add_u32_e32 v172, 0x1000, v172
	v_add_u32_e32 v159, 0x1200, v159
	s_branch .Lat_top

.Lat_full:
	v_xor_b32_e32 v172, 64, v158
	ds_read_b128 v[204:207], v159
	ds_read_b128 v[208:211], v159 offset:32
	ds_read_b128 v[212:215], v159 offset:64
	ds_read_b128 v[232:235], v159 offset:96
	s_waitcnt lgkmcnt(3)
	v_mfma_f32_32x32x16_bf16 v[62:77], v[204:207], v[110:113], v[32:47]
	s_waitcnt lgkmcnt(2)
	v_mfma_f32_32x32x16_bf16 v[62:77], v[208:211], v[114:117], v[62:77]
	s_waitcnt lgkmcnt(1)
	v_mfma_f32_32x32x16_bf16 v[62:77], v[212:215], v[118:121], v[62:77]
	s_waitcnt lgkmcnt(0)
	v_mfma_f32_32x32x16_bf16 v[62:77], v[232:235], v[122:125], v[62:77]
	ds_read_b128 v[204:207], v159 offset:4608
	ds_read_b128 v[208:211], v159 offset:4640
	ds_read_b128 v[212:215], v159 offset:4672
	ds_read_b128 v[232:235], v159 offset:4704
	s_nop 7
	s_nop 3
	v_exp_f32_e32 v48, v62
	v_exp_f32_e32 v49, v63
	v_exp_f32_e32 v50, v64
	v_exp_f32_e32 v51, v65
	v_exp_f32_e32 v52, v66
	v_exp_f32_e32 v53, v67
	v_exp_f32_e32 v54, v68
	v_exp_f32_e32 v55, v69
	v_exp_f32_e32 v56, v70
	v_exp_f32_e32 v57, v71
	v_exp_f32_e32 v58, v72
	v_exp_f32_e32 v59, v73
	v_exp_f32_e32 v60, v74
	v_exp_f32_e32 v61, v75
	v_exp_f32_e32 v216, v76
	v_exp_f32_e32 v217, v77
	ds_read_b64_tr_b16 v[236:237], v158
	ds_read_b64_tr_b16 v[238:239], v158 offset:1024
	ds_read_b64_tr_b16 v[240:241], v158 offset:2048
	ds_read_b64_tr_b16 v[242:243], v158 offset:3072
	ds_read_b64_tr_b16 v[164:165], v172
	ds_read_b64_tr_b16 v[166:167], v172 offset:1024
	ds_read_b64_tr_b16 v[168:169], v172 offset:2048
	ds_read_b64_tr_b16 v[170:171], v172 offset:3072
	s_waitcnt lgkmcnt(11)
	v_mfma_f32_32x32x16_bf16 v[62:77], v[204:207], v[110:113], v[32:47]
	v_pk_add_f32 v[218:219], v[48:49], v[50:51]
	v_pk_add_f32 v[244:245], v[52:53], v[54:55]
	v_pk_add_f32 v[198:199], v[56:57], v[58:59]
	v_pk_add_f32 v[200:201], v[60:61], v[216:217]
	s_waitcnt lgkmcnt(10)
	v_mfma_f32_32x32x16_bf16 v[62:77], v[208:211], v[114:117], v[62:77]
	v_cvt_pk_bf16_f32 v220, v48, v49
	v_cvt_pk_bf16_f32 v221, v50, v51
	v_cvt_pk_bf16_f32 v222, v52, v53
	v_cvt_pk_bf16_f32 v223, v54, v55
	v_pk_add_f32 v[218:219], v[218:219], v[244:245]
	v_pk_add_f32 v[198:199], v[198:199], v[200:201]
	s_waitcnt lgkmcnt(9)
	v_mfma_f32_32x32x16_bf16 v[62:77], v[212:215], v[118:121], v[62:77]
	v_cvt_pk_bf16_f32 v224, v56, v57
	v_cvt_pk_bf16_f32 v225, v58, v59
	v_cvt_pk_bf16_f32 v226, v60, v61
	v_cvt_pk_bf16_f32 v227, v216, v217
	v_pk_add_f32 v[218:219], v[218:219], v[198:199]
	s_waitcnt lgkmcnt(8)
	v_mfma_f32_32x32x16_bf16 v[62:77], v[232:235], v[122:125], v[62:77]
	v_add_f32_e32 v218, v218, v219
	v_add_f32_e32 v155, v155, v218
	ds_read_b128 v[204:207], v159 offset:9216
	ds_read_b128 v[208:211], v159 offset:9248
	ds_read_b128 v[212:215], v159 offset:9280
	ds_read_b128 v[232:235], v159 offset:9312
	s_nop 3
	s_waitcnt lgkmcnt(4)
	v_mfma_f32_32x32x16_bf16 v[16:31], v[236:239], v[220:223], v[16:31]
	v_exp_f32_e32 v48, v62
	v_exp_f32_e32 v49, v63
	v_exp_f32_e32 v50, v64
	v_exp_f32_e32 v51, v65
	v_mfma_f32_32x32x16_bf16 v[0:15], v[164:167], v[220:223], v[0:15]
	v_exp_f32_e32 v52, v66
	v_exp_f32_e32 v53, v67
	v_exp_f32_e32 v54, v68
	v_exp_f32_e32 v55, v69
	v_mfma_f32_32x32x16_bf16 v[16:31], v[240:243], v[224:227], v[16:31]
	v_exp_f32_e32 v56, v70
	v_exp_f32_e32 v57, v71
	v_exp_f32_e32 v58, v72
	v_exp_f32_e32 v59, v73
	v_mfma_f32_32x32x16_bf16 v[0:15], v[168:171], v[224:227], v[0:15]
	v_exp_f32_e32 v60, v74
	v_exp_f32_e32 v61, v75
	v_exp_f32_e32 v216, v76
	v_exp_f32_e32 v217, v77
	ds_read_b64_tr_b16 v[236:237], v158 offset:4096
	ds_read_b64_tr_b16 v[238:239], v158 offset:5120
	ds_read_b64_tr_b16 v[240:241], v158 offset:6144
	ds_read_b64_tr_b16 v[242:243], v158 offset:7168
	ds_read_b64_tr_b16 v[164:165], v172 offset:4096
	ds_read_b64_tr_b16 v[166:167], v172 offset:5120
	ds_read_b64_tr_b16 v[168:169], v172 offset:6144
	ds_read_b64_tr_b16 v[170:171], v172 offset:7168
	s_waitcnt lgkmcnt(11)
	v_mfma_f32_32x32x16_bf16 v[62:77], v[204:207], v[110:113], v[32:47]
	v_pk_add_f32 v[218:219], v[48:49], v[50:51]
	v_pk_add_f32 v[244:245], v[52:53], v[54:55]
	v_pk_add_f32 v[198:199], v[56:57], v[58:59]
	v_pk_add_f32 v[200:201], v[60:61], v[216:217]
	s_waitcnt lgkmcnt(10)
	v_mfma_f32_32x32x16_bf16 v[62:77], v[208:211], v[114:117], v[62:77]
	v_cvt_pk_bf16_f32 v220, v48, v49
	v_cvt_pk_bf16_f32 v221, v50, v51
	v_cvt_pk_bf16_f32 v222, v52, v53
	v_cvt_pk_bf16_f32 v223, v54, v55
	v_pk_add_f32 v[218:219], v[218:219], v[244:245]
	v_pk_add_f32 v[198:199], v[198:199], v[200:201]
	s_waitcnt lgkmcnt(9)
	v_mfma_f32_32x32x16_bf16 v[62:77], v[212:215], v[118:121], v[62:77]
	v_cvt_pk_bf16_f32 v224, v56, v57
	v_cvt_pk_bf16_f32 v225, v58, v59
	v_cvt_pk_bf16_f32 v226, v60, v61
	v_cvt_pk_bf16_f32 v227, v216, v217
	v_pk_add_f32 v[218:219], v[218:219], v[198:199]
	s_waitcnt lgkmcnt(8)
	v_mfma_f32_32x32x16_bf16 v[62:77], v[232:235], v[122:125], v[62:77]
	v_add_f32_e32 v218, v218, v219
	v_add_f32_e32 v155, v155, v218
	ds_read_b128 v[204:207], v159 offset:13824
	ds_read_b128 v[208:211], v159 offset:13856
	ds_read_b128 v[212:215], v159 offset:13888
	ds_read_b128 v[232:235], v159 offset:13920
	s_nop 3
	s_waitcnt lgkmcnt(4)
	v_mfma_f32_32x32x16_bf16 v[16:31], v[236:239], v[220:223], v[16:31]
	v_exp_f32_e32 v48, v62
	v_exp_f32_e32 v49, v63
	v_exp_f32_e32 v50, v64
	v_exp_f32_e32 v51, v65
	v_mfma_f32_32x32x16_bf16 v[0:15], v[164:167], v[220:223], v[0:15]
	v_exp_f32_e32 v52, v66
	v_exp_f32_e32 v53, v67
	v_exp_f32_e32 v54, v68
	v_exp_f32_e32 v55, v69
	v_mfma_f32_32x32x16_bf16 v[16:31], v[240:243], v[224:227], v[16:31]
	v_exp_f32_e32 v56, v70
	v_exp_f32_e32 v57, v71
	v_exp_f32_e32 v58, v72
	v_exp_f32_e32 v59, v73
	v_mfma_f32_32x32x16_bf16 v[0:15], v[168:171], v[224:227], v[0:15]
	v_exp_f32_e32 v60, v74
	v_exp_f32_e32 v61, v75
	v_exp_f32_e32 v216, v76
	v_exp_f32_e32 v217, v77
	ds_read_b64_tr_b16 v[236:237], v158 offset:8192
	ds_read_b64_tr_b16 v[238:239], v158 offset:9216
	ds_read_b64_tr_b16 v[240:241], v158 offset:10240
	ds_read_b64_tr_b16 v[242:243], v158 offset:11264
	ds_read_b64_tr_b16 v[164:165], v172 offset:8192
	ds_read_b64_tr_b16 v[166:167], v172 offset:9216
	ds_read_b64_tr_b16 v[168:169], v172 offset:10240
	ds_read_b64_tr_b16 v[170:171], v172 offset:11264
	s_waitcnt lgkmcnt(11)
	v_mfma_f32_32x32x16_bf16 v[62:77], v[204:207], v[110:113], v[32:47]
	v_pk_add_f32 v[218:219], v[48:49], v[50:51]
	v_pk_add_f32 v[244:245], v[52:53], v[54:55]
	v_pk_add_f32 v[198:199], v[56:57], v[58:59]
	v_pk_add_f32 v[200:201], v[60:61], v[216:217]
	s_waitcnt lgkmcnt(10)
	v_mfma_f32_32x32x16_bf16 v[62:77], v[208:211], v[114:117], v[62:77]
	v_cvt_pk_bf16_f32 v220, v48, v49
	v_cvt_pk_bf16_f32 v221, v50, v51
	v_cvt_pk_bf16_f32 v222, v52, v53
	v_cvt_pk_bf16_f32 v223, v54, v55
	v_pk_add_f32 v[218:219], v[218:219], v[244:245]
	v_pk_add_f32 v[198:199], v[198:199], v[200:201]
	s_waitcnt lgkmcnt(9)
	v_mfma_f32_32x32x16_bf16 v[62:77], v[212:215], v[118:121], v[62:77]
	v_cvt_pk_bf16_f32 v224, v56, v57
	v_cvt_pk_bf16_f32 v225, v58, v59
	v_cvt_pk_bf16_f32 v226, v60, v61
	v_cvt_pk_bf16_f32 v227, v216, v217
	v_pk_add_f32 v[218:219], v[218:219], v[198:199]
	s_waitcnt lgkmcnt(8)
	v_mfma_f32_32x32x16_bf16 v[62:77], v[232:235], v[122:125], v[62:77]
	v_add_f32_e32 v218, v218, v219
	v_add_f32_e32 v155, v155, v218
	s_nop 7
	s_waitcnt lgkmcnt(0)
	v_mfma_f32_32x32x16_bf16 v[16:31], v[236:239], v[220:223], v[16:31]
	v_exp_f32_e32 v48, v62
	v_exp_f32_e32 v49, v63
	v_exp_f32_e32 v50, v64
	v_exp_f32_e32 v51, v65
	v_mfma_f32_32x32x16_bf16 v[0:15], v[164:167], v[220:223], v[0:15]
	v_exp_f32_e32 v52, v66
	v_exp_f32_e32 v53, v67
	v_exp_f32_e32 v54, v68
	v_exp_f32_e32 v55, v69
	v_mfma_f32_32x32x16_bf16 v[16:31], v[240:243], v[224:227], v[16:31]
	v_exp_f32_e32 v56, v70
	v_exp_f32_e32 v57, v71
	v_exp_f32_e32 v58, v72
	v_exp_f32_e32 v59, v73
	v_mfma_f32_32x32x16_bf16 v[0:15], v[168:171], v[224:227], v[0:15]
	v_exp_f32_e32 v60, v74
	v_exp_f32_e32 v61, v75
	v_exp_f32_e32 v216, v76
	v_exp_f32_e32 v217, v77
	ds_read_b64_tr_b16 v[236:237], v158 offset:12288
	ds_read_b64_tr_b16 v[238:239], v158 offset:13312
	ds_read_b64_tr_b16 v[240:241], v158 offset:14336
	ds_read_b64_tr_b16 v[242:243], v158 offset:15360
	ds_read_b64_tr_b16 v[164:165], v172 offset:12288
	ds_read_b64_tr_b16 v[166:167], v172 offset:13312
	ds_read_b64_tr_b16 v[168:169], v172 offset:14336
	ds_read_b64_tr_b16 v[170:171], v172 offset:15360
	v_pk_add_f32 v[218:219], v[48:49], v[50:51]
	v_pk_add_f32 v[244:245], v[52:53], v[54:55]
	v_pk_add_f32 v[198:199], v[56:57], v[58:59]
	v_pk_add_f32 v[200:201], v[60:61], v[216:217]
	v_cvt_pk_bf16_f32 v220, v48, v49
	v_cvt_pk_bf16_f32 v221, v50, v51
	v_cvt_pk_bf16_f32 v222, v52, v53
	v_cvt_pk_bf16_f32 v223, v54, v55
	v_pk_add_f32 v[218:219], v[218:219], v[244:245]
	v_pk_add_f32 v[198:199], v[198:199], v[200:201]
	v_cvt_pk_bf16_f32 v224, v56, v57
	v_cvt_pk_bf16_f32 v225, v58, v59
	v_cvt_pk_bf16_f32 v226, v60, v61
	v_cvt_pk_bf16_f32 v227, v216, v217
	v_pk_add_f32 v[218:219], v[218:219], v[198:199]
	v_add_f32_e32 v218, v218, v219
	v_add_f32_e32 v155, v155, v218
	s_waitcnt lgkmcnt(0)
	v_mfma_f32_32x32x16_bf16 v[16:31], v[236:239], v[220:223], v[16:31]
	v_mfma_f32_32x32x16_bf16 v[0:15], v[164:167], v[220:223], v[0:15]
	v_mfma_f32_32x32x16_bf16 v[16:31], v[240:243], v[224:227], v[16:31]
	v_mfma_f32_32x32x16_bf16 v[0:15], v[168:171], v[224:227], v[0:15]
	s_branch .LBB0_84

.Lkc3_st:
	global_store_dwordx4 v127, v[110:113], s[2:3]
	global_store_dwordx4 v127, v[114:117], s[2:3] offset:16
	global_store_dwordx4 v127, v[118:121], s[2:3] offset:32
	global_store_dwordx4 v127, v[122:125], s[2:3] offset:48
	v_lshl_add_u32 v34, v212, 2, s33
	ds_read2st64_b32 v[32:33], v34 offset0:204 offset1:206
	v_bfe_u32 v36, v212, 1, 1
	v_xor_b32_e32 v36, v36, v213
	v_lshlrev_b32_e32 v36, 6, v36
	v_lshl_add_u32 v37, v212, 7, s33
	v_add_u32_e32 v37, v37, v36
	s_waitcnt lgkmcnt(0)
	v_pk_mul_f32 v[132:133], v[58:59], v[32:33] op_sel_hi:[1,0]
	v_pk_mul_f32 v[134:135], v[88:89], v[32:33] op_sel_hi:[1,0]
	v_pk_mul_f32 v[136:137], v[78:79], v[32:33] op_sel_hi:[1,0]
	v_pk_mul_f32 v[138:139], v[76:77], v[32:33] op_sel_hi:[1,0]
	v_pk_mul_f32 v[140:141], v[80:81], v[32:33] op_sel_hi:[1,0]
	v_pk_mul_f32 v[142:143], v[84:85], v[32:33] op_sel_hi:[1,0]
	v_pk_mul_f32 v[144:145], v[82:83], v[32:33] op_sel_hi:[1,0]
	v_pk_mul_f32 v[146:147], v[56:57], v[32:33] op_sel_hi:[1,0]
	v_pk_mul_f32 v[148:149], v[18:19], v[32:33] op_sel_hi:[1,0]
	v_pk_mul_f32 v[150:151], v[26:27], v[32:33] op_sel_hi:[1,0]
	v_pk_mul_f32 v[152:153], v[24:25], v[32:33] op_sel_hi:[1,0]
	v_pk_mul_f32 v[154:155], v[16:17], v[32:33] op_sel_hi:[1,0]
	v_pk_mul_f32 v[156:157], v[20:21], v[32:33] op_sel_hi:[1,0]
	v_pk_mul_f32 v[158:159], v[22:23], v[32:33] op_sel_hi:[1,0]
	v_pk_mul_f32 v[164:165], v[28:29], v[32:33] op_sel_hi:[1,0]
	v_pk_mul_f32 v[166:167], v[30:31], v[32:33] op_sel_hi:[1,0]
	v_cvt_pk_bf16_f32 v168, v132, v133
	v_cvt_pk_bf16_f32 v169, v134, v135
	v_cvt_pk_bf16_f32 v170, v136, v137
	v_cvt_pk_bf16_f32 v171, v138, v139
	v_cvt_pk_bf16_f32 v172, v140, v141
	v_cvt_pk_bf16_f32 v173, v142, v143
	v_cvt_pk_bf16_f32 v174, v144, v145
	v_cvt_pk_bf16_f32 v175, v146, v147
	v_cvt_pk_bf16_f32 v198, v148, v149
	v_cvt_pk_bf16_f32 v199, v150, v151
	v_cvt_pk_bf16_f32 v200, v152, v153
	v_cvt_pk_bf16_f32 v201, v154, v155
	v_cvt_pk_bf16_f32 v202, v156, v157
	v_cvt_pk_bf16_f32 v203, v158, v159
	v_cvt_pk_bf16_f32 v204, v164, v165
	v_cvt_pk_bf16_f32 v205, v166, v167
	ds_write_b128 v37, v[168:171] offset:0
	ds_write_b128 v37, v[172:175] offset:16
	ds_write_b128 v37, v[198:201] offset:32
	ds_write_b128 v37, v[202:205] offset:48
	v_pk_mul_f32 v[132:133], v[58:59], v[32:33] op_sel:[0,1] op_sel_hi:[1,1]
	v_pk_mul_f32 v[134:135], v[88:89], v[32:33] op_sel:[0,1] op_sel_hi:[1,1]
	v_pk_mul_f32 v[136:137], v[78:79], v[32:33] op_sel:[0,1] op_sel_hi:[1,1]
	v_pk_mul_f32 v[138:139], v[76:77], v[32:33] op_sel:[0,1] op_sel_hi:[1,1]
	v_pk_mul_f32 v[140:141], v[80:81], v[32:33] op_sel:[0,1] op_sel_hi:[1,1]
	v_pk_mul_f32 v[142:143], v[84:85], v[32:33] op_sel:[0,1] op_sel_hi:[1,1]
	v_pk_mul_f32 v[144:145], v[82:83], v[32:33] op_sel:[0,1] op_sel_hi:[1,1]
	v_pk_mul_f32 v[146:147], v[56:57], v[32:33] op_sel:[0,1] op_sel_hi:[1,1]
	v_pk_mul_f32 v[148:149], v[18:19], v[32:33] op_sel:[0,1] op_sel_hi:[1,1]
	v_pk_mul_f32 v[150:151], v[26:27], v[32:33] op_sel:[0,1] op_sel_hi:[1,1]
	v_pk_mul_f32 v[152:153], v[24:25], v[32:33] op_sel:[0,1] op_sel_hi:[1,1]
	v_pk_mul_f32 v[154:155], v[16:17], v[32:33] op_sel:[0,1] op_sel_hi:[1,1]
	v_pk_mul_f32 v[156:157], v[20:21], v[32:33] op_sel:[0,1] op_sel_hi:[1,1]
	v_pk_mul_f32 v[158:159], v[22:23], v[32:33] op_sel:[0,1] op_sel_hi:[1,1]
	v_pk_mul_f32 v[164:165], v[28:29], v[32:33] op_sel:[0,1] op_sel_hi:[1,1]
	v_pk_mul_f32 v[166:167], v[30:31], v[32:33] op_sel:[0,1] op_sel_hi:[1,1]
	v_cvt_pk_bf16_f32 v214, v132, v133
	v_cvt_pk_bf16_f32 v215, v134, v135
	v_cvt_pk_bf16_f32 v216, v136, v137
	v_cvt_pk_bf16_f32 v217, v138, v139
	v_cvt_pk_bf16_f32 v218, v140, v141
	v_cvt_pk_bf16_f32 v219, v142, v143
	v_cvt_pk_bf16_f32 v220, v144, v145
	v_cvt_pk_bf16_f32 v221, v146, v147
	v_cvt_pk_bf16_f32 v222, v148, v149
	v_cvt_pk_bf16_f32 v223, v150, v151
	v_cvt_pk_bf16_f32 v224, v152, v153
	v_cvt_pk_bf16_f32 v225, v154, v155
	v_cvt_pk_bf16_f32 v226, v156, v157
	v_cvt_pk_bf16_f32 v227, v158, v159
	v_cvt_pk_bf16_f32 v228, v164, v165
	v_cvt_pk_bf16_f32 v229, v166, v167
	ds_write_b128 v37, v[214:217] offset:16384
	ds_write_b128 v37, v[218:221] offset:16400
	ds_write_b128 v37, v[222:225] offset:16416
	ds_write_b128 v37, v[226:229] offset:16432
	s_waitcnt vmcnt(4)
	ds_write_b128 v37, v[12:15] offset:32768
	ds_write_b128 v37, v[8:11] offset:32784
	ds_write_b128 v37, v[4:7] offset:32800
	ds_write_b128 v37, v[0:3] offset:32816
	s_nop 1
	v_lshrrev_b32_e32 v3, 2, v211
	v_bfe_u32 v0, v209, 6, 1
	v_and_b32_e32 v1, 31, v211
	v_and_b32_e32 v3, 32, v3
	v_or_b32_e32 v4, v3, v1
	v_lshl_or_b32 v5, v0, 5, v1
	v_lshlrev_b32_e32 v1, 7, v1
	v_lshl_or_b32 v160, v0, 12, v1
	s_bfe_u32 s1, s38, 0x10003
	v_lshrrev_b32_e32 v2, 5, v208
	v_lshl_add_u64 v[0:1], s[20:21], 0, v[160:161]
	v_lshlrev_b32_e32 v160, 1, v3
	s_and_b64 s[2:3], s[26:27], exec
	v_lshl_add_u64 v[0:1], v[0:1], 0, v[160:161]
	v_lshlrev_b32_e32 v160, 3, v2
	v_lshl_add_u64 v[24:25], v[0:1], 0, v[160:161]
	v_lshl_add_u32 v0, v2, 4, s33
	s_movk_i32 s2, 0x110
	v_mad_u32_u24 v54, v4, s2, v0
	v_and_b32_e32 v58, 15, v208
	v_lshrrev_b32_e32 v58, 2, v58
	v_lshrrev_b32_e32 v59, 5, v208
	v_lshl_add_u32 v59, v59, 2, v58
	v_lshl_add_u32 v59, v59, 7, s33
	v_bfe_u32 v56, v208, 4, 1
	v_lshlrev_b32_e32 v56, 5, v56
	v_and_b32_e32 v57, 3, v208
	v_lshl_add_u32 v56, v57, 3, v56
	v_add_u32_e32 v59, v59, v56
	v_lshrrev_b32_e32 v58, 1, v58
	v_bfe_u32 v56, v209, 7, 1
	v_xor_b32_e32 v56, v56, v58
	v_lshl_add_u32 v56, v56, 6, v59
	v_bfe_u32 v57, v209, 6, 1
	v_xor_b32_e32 v57, v57, v58
	v_lshl_add_u32 v57, v57, 6, v59
	v_add_u32_e32 v57, 0x8000, v57
	s_waitcnt lgkmcnt(0)
	s_barrier
	v_mad_u32_u24 v55, v5, s2, v0
	ds_read_b64_tr_b16 v[60:61], v56
	ds_read_b64_tr_b16 v[62:63], v56 offset:1024
	ds_read_b64_tr_b16 v[26:27], v57
	ds_read_b64_tr_b16 v[28:29], v57 offset:1024
	ds_read_b64_tr_b16 v[64:65], v56 offset:2048
	ds_read_b64_tr_b16 v[66:67], v56 offset:3072
	ds_read_b64_tr_b16 v[30:31], v57 offset:2048
	ds_read_b64_tr_b16 v[32:33], v57 offset:3072
	ds_read_b64_tr_b16 v[68:69], v56 offset:4096
	ds_read_b64_tr_b16 v[70:71], v56 offset:5120
	ds_read_b64_tr_b16 v[34:35], v57 offset:4096
	ds_read_b64_tr_b16 v[36:37], v57 offset:5120
	s_waitcnt lgkmcnt(8)
	v_mfma_f32_32x32x16_bf16 v[0:15], v[60:63], v[26:29], 0
	s_cselect_b32 s0, 0x43, 1
	s_lshl_b32 s2, s1, 5
	ds_read_b64_tr_b16 v[72:73], v56 offset:6144
	ds_read_b64_tr_b16 v[74:75], v56 offset:7168
	ds_read_b64_tr_b16 v[38:39], v57 offset:6144
	ds_read_b64_tr_b16 v[40:41], v57 offset:7168
	s_waitcnt lgkmcnt(8)
	v_mfma_f32_32x32x16_bf16 v[0:15], v[64:67], v[30:33], v[0:15]
	s_lshl_b32 s3, s36, 3
	s_add_i32 s2, s2, s3
	ds_read_b64_tr_b16 v[132:133], v56 offset:8192
	ds_read_b64_tr_b16 v[134:135], v56 offset:9216
	ds_read_b64_tr_b16 v[42:43], v57 offset:8192
	ds_read_b64_tr_b16 v[44:45], v57 offset:9216
	s_waitcnt lgkmcnt(8)
	v_mfma_f32_32x32x16_bf16 v[0:15], v[68:71], v[34:37], v[0:15]
	s_or_b32 s2, s2, s37
	s_sub_i32 s0, s0, s35
	ds_read_b64_tr_b16 v[136:137], v56 offset:10240
	ds_read_b64_tr_b16 v[138:139], v56 offset:11264
	ds_read_b64_tr_b16 v[46:47], v57 offset:10240
	ds_read_b64_tr_b16 v[48:49], v57 offset:11264
	s_waitcnt lgkmcnt(8)
	v_mfma_f32_32x32x16_bf16 v[0:15], v[72:75], v[38:41], v[0:15]
	s_mul_i32 s3, s2, 0x42
	s_ashr_i32 s6, s35, 31
	ds_read_b64_tr_b16 v[140:141], v56 offset:12288
	ds_read_b64_tr_b16 v[142:143], v56 offset:13312
	ds_read_b64_tr_b16 v[20:21], v57 offset:12288
	ds_read_b64_tr_b16 v[22:23], v57 offset:13312
	s_waitcnt lgkmcnt(8)
	v_mfma_f32_32x32x16_bf16 v[0:15], v[132:135], v[42:45], v[0:15]
	s_mul_hi_i32 s5, s2, 0x42
	s_add_u32 s4, s3, s35
	ds_read_b64_tr_b16 v[144:145], v56 offset:14336
	ds_read_b64_tr_b16 v[146:147], v56 offset:15360
	ds_read_b64_tr_b16 v[16:17], v57 offset:14336
	ds_read_b64_tr_b16 v[18:19], v57 offset:15360
	s_waitcnt lgkmcnt(8)
	v_mfma_f32_32x32x16_bf16 v[0:15], v[136:139], v[46:49], v[0:15]
	s_addc_u32 s5, s5, s6
	s_lshl_b64 s[4:5], s[4:5], 13
	ds_read_b64_tr_b16 v[148:149], v56 offset:16384
	ds_read_b64_tr_b16 v[150:151], v56 offset:17408
	ds_read_b64_tr_b16 v[152:153], v56 offset:18432
	ds_read_b64_tr_b16 v[154:155], v56 offset:19456
	s_waitcnt lgkmcnt(8)
	v_mfma_f32_32x32x16_bf16 v[0:15], v[140:143], v[20:23], v[0:15]
	s_add_i32 s2, s2, 16
	s_addk_i32 s3, 0x420
	ds_read_b64_tr_b16 v[156:157], v56 offset:20480
	ds_read_b64_tr_b16 v[158:159], v56 offset:21504
	ds_read_b64_tr_b16 v[164:165], v56 offset:22528
	ds_read_b64_tr_b16 v[166:167], v56 offset:23552
	s_waitcnt lgkmcnt(8)
	v_mfma_f32_32x32x16_bf16 v[0:15], v[144:147], v[16:19], v[0:15]
	v_lshl_add_u64 v[50:51], v[24:25], 0, s[4:5]
	s_mul_hi_i32 s4, s2, 0x42
	s_add_u32 s2, s3, s0
	s_addc_u32 s3, s4, 0
	s_lshl_b64 s[2:3], s[2:3], 13
	s_cmp_lg_u32 s1, 0
	s_movk_i32 s1, 0x80
	s_nop 4
	v_cvt_pk_bf16_f32 v0, v0, v1
	v_cvt_pk_bf16_f32 v1, v2, v3
	v_cvt_pk_bf16_f32 v2, v4, v5
	v_cvt_pk_bf16_f32 v3, v6, v7
	v_cvt_pk_bf16_f32 v4, v8, v9
	v_cvt_pk_bf16_f32 v5, v10, v11
	v_cvt_pk_bf16_f32 v6, v12, v13
	v_cvt_pk_bf16_f32 v7, v14, v15
	v_mbcnt_lo_u32_b32 v8, -1, 0
	v_mbcnt_hi_u32_b32 v8, -1, v8
	v_lshrrev_b32_e32 v8, 2, v8
	v_and_b32_e32 v8, 8, v8
	v_mov_b32_e32 v9, 0
	v_permlane32_swap_b32_e32 v0, v2
	v_permlane32_swap_b32_e32 v1, v3
	v_permlane32_swap_b32_e32 v4, v6
	v_permlane32_swap_b32_e32 v5, v7
	v_lshl_add_u64 v[50:51], v[50:51], 0, v[8:9]
	global_store_dwordx4 v[50:51], v[0:3], off
	global_store_dwordx4 v[50:51], v[4:7], off offset:32
	s_nop 1
	ds_read_b64_tr_b16 v[168:169], v56 offset:24576
	ds_read_b64_tr_b16 v[170:171], v56 offset:25600
	s_waitcnt lgkmcnt(8)
	v_mfma_f32_32x32x16_bf16 v[0:15], v[148:151], v[26:29], 0
	ds_read_b64_tr_b16 v[172:173], v56 offset:26624
	ds_read_b64_tr_b16 v[174:175], v56 offset:27648
	s_waitcnt lgkmcnt(8)
	v_mfma_f32_32x32x16_bf16 v[0:15], v[152:155], v[30:33], v[0:15]
	v_cmp_gt_u32_e32 vcc, s1, v209
	ds_read_b64_tr_b16 v[200:201], v56 offset:28672
	ds_read_b64_tr_b16 v[202:203], v56 offset:29696
	s_waitcnt lgkmcnt(8)
	v_mfma_f32_32x32x16_bf16 v[0:15], v[156:159], v[34:37], v[0:15]
	ds_read_b64_tr_b16 v[204:205], v56 offset:30720
	ds_read_b64_tr_b16 v[206:207], v56 offset:31744
	s_waitcnt lgkmcnt(8)
	v_mfma_f32_32x32x16_bf16 v[0:15], v[164:167], v[38:41], v[0:15]
	s_waitcnt lgkmcnt(6)
	v_mfma_f32_32x32x16_bf16 v[0:15], v[168:171], v[42:45], v[0:15]
	s_waitcnt lgkmcnt(4)
	v_mfma_f32_32x32x16_bf16 v[0:15], v[172:175], v[46:49], v[0:15]
	s_waitcnt lgkmcnt(2)
	v_mfma_f32_32x32x16_bf16 v[0:15], v[200:203], v[20:23], v[0:15]
	s_waitcnt lgkmcnt(0)
	v_mfma_f32_32x32x16_bf16 v[0:15], v[204:207], v[16:19], v[0:15]
	v_lshl_add_u64 v[16:17], v[24:25], 0, s[2:3]
	s_cselect_b64 s[2:3], -1, 0
	s_and_b64 s[2:3], s[2:3], vcc
	s_nop 8
	v_cvt_pk_bf16_f32 v0, v0, v1
	v_cvt_pk_bf16_f32 v1, v2, v3
	v_cvt_pk_bf16_f32 v2, v4, v5
	v_cvt_pk_bf16_f32 v3, v6, v7
	v_cvt_pk_bf16_f32 v4, v8, v9
	v_cvt_pk_bf16_f32 v5, v10, v11
	v_cvt_pk_bf16_f32 v6, v12, v13
	v_cvt_pk_bf16_f32 v7, v14, v15
	v_mbcnt_lo_u32_b32 v8, -1, 0
	v_mbcnt_hi_u32_b32 v8, -1, v8
	v_lshrrev_b32_e32 v8, 2, v8
	v_and_b32_e32 v8, 8, v8
	v_mov_b32_e32 v9, 0
	v_permlane32_swap_b32_e32 v0, v2
	v_permlane32_swap_b32_e32 v1, v3
	v_permlane32_swap_b32_e32 v4, v6
	v_permlane32_swap_b32_e32 v5, v7
	v_lshl_add_u64 v[16:17], v[16:17], 0, v[8:9]
	global_store_dwordx4 v[16:17], v[0:3], off
	global_store_dwordx4 v[16:17], v[4:7], off offset:32
	s_nop 1
	s_and_saveexec_b64 s[4:5], s[2:3]
	s_cbranch_execz .LBB0_958
	v_cmp_gt_u32_e32 vcc, 64, v209
	v_and_b32_e32 v18, 15, v208
	v_lshrrev_b32_e32 v18, 2, v18
	v_lshrrev_b32_e32 v19, 4, v208
	v_lshrrev_b32_e32 v20, 1, v18
	v_lshrrev_b32_e32 v21, 1, v19
	v_xor_b32_e32 v20, v20, v21
	v_lshlrev_b32_e32 v20, 6, v20
	v_lshl_add_u32 v20, v18, 7, v20
	v_and_b32_e32 v19, 1, v19
	v_lshl_add_u32 v20, v19, 5, v20
	v_and_b32_e32 v19, 3, v208
	v_lshl_add_u32 v20, v19, 3, v20
	v_bfe_u32 v19, v211, 6, 1
	v_lshl_add_u32 v20, v19, 14, v20
	v_add_u32_e32 v16, s33, v20
	v_mov_b32_e32 v17, 0
	ds_read_b64_tr_b16 v[0:1], v16
	ds_read_b64_tr_b16 v[2:3], v16 offset:512
	ds_read_b64_tr_b16 v[4:5], v16 offset:1024
	ds_read_b64_tr_b16 v[6:7], v16 offset:1536
	ds_read_b64_tr_b16 v[8:9], v16 offset:2048
	ds_read_b64_tr_b16 v[10:11], v16 offset:2560
	ds_read_b64_tr_b16 v[12:13], v16 offset:3072
	ds_read_b64_tr_b16 v[14:15], v16 offset:3584
	s_waitcnt lgkmcnt(7)
	v_lshlrev_b32_e32 v18, 16, v0
	v_and_b32_e32 v19, 0xffff0000, v0
	v_add_f32_e32 v17, v17, v18
	v_add_f32_e32 v17, v17, v19
	v_lshlrev_b32_e32 v18, 16, v1
	v_and_b32_e32 v19, 0xffff0000, v1
	v_add_f32_e32 v17, v17, v18
	v_add_f32_e32 v17, v17, v19
	s_waitcnt lgkmcnt(6)
	v_lshlrev_b32_e32 v18, 16, v2
	v_and_b32_e32 v19, 0xffff0000, v2
	v_add_f32_e32 v17, v17, v18
	v_add_f32_e32 v17, v17, v19
	v_lshlrev_b32_e32 v18, 16, v3
	v_and_b32_e32 v19, 0xffff0000, v3
	v_add_f32_e32 v17, v17, v18
	v_add_f32_e32 v17, v17, v19
	s_waitcnt lgkmcnt(5)
	v_lshlrev_b32_e32 v18, 16, v4
	v_and_b32_e32 v19, 0xffff0000, v4
	v_add_f32_e32 v17, v17, v18
	v_add_f32_e32 v17, v17, v19
	v_lshlrev_b32_e32 v18, 16, v5
	v_and_b32_e32 v19, 0xffff0000, v5
	v_add_f32_e32 v17, v17, v18
	v_add_f32_e32 v17, v17, v19
	s_waitcnt lgkmcnt(4)
	v_lshlrev_b32_e32 v18, 16, v6
	v_and_b32_e32 v19, 0xffff0000, v6
	v_add_f32_e32 v17, v17, v18
	v_add_f32_e32 v17, v17, v19
	v_lshlrev_b32_e32 v18, 16, v7
	v_and_b32_e32 v19, 0xffff0000, v7
	v_add_f32_e32 v17, v17, v18
	v_add_f32_e32 v17, v17, v19
	s_waitcnt lgkmcnt(3)
	v_lshlrev_b32_e32 v18, 16, v8
	v_and_b32_e32 v19, 0xffff0000, v8
	v_add_f32_e32 v17, v17, v18
	v_add_f32_e32 v17, v17, v19
	v_lshlrev_b32_e32 v18, 16, v9
	v_and_b32_e32 v19, 0xffff0000, v9
	v_add_f32_e32 v17, v17, v18
	v_add_f32_e32 v17, v17, v19
	s_waitcnt lgkmcnt(2)
	v_lshlrev_b32_e32 v18, 16, v10
	v_and_b32_e32 v19, 0xffff0000, v10
	v_add_f32_e32 v17, v17, v18
	v_add_f32_e32 v17, v17, v19
	v_lshlrev_b32_e32 v18, 16, v11
	v_and_b32_e32 v19, 0xffff0000, v11
	v_add_f32_e32 v17, v17, v18
	v_add_f32_e32 v17, v17, v19
	s_waitcnt lgkmcnt(1)
	v_lshlrev_b32_e32 v18, 16, v12
	v_and_b32_e32 v19, 0xffff0000, v12
	v_add_f32_e32 v17, v17, v18
	v_add_f32_e32 v17, v17, v19
	v_lshlrev_b32_e32 v18, 16, v13
	v_and_b32_e32 v19, 0xffff0000, v13
	v_add_f32_e32 v17, v17, v18
	v_add_f32_e32 v17, v17, v19
	s_waitcnt lgkmcnt(0)
	v_lshlrev_b32_e32 v18, 16, v14
	v_and_b32_e32 v19, 0xffff0000, v14
	v_add_f32_e32 v17, v17, v18
	v_add_f32_e32 v17, v17, v19
	v_lshlrev_b32_e32 v18, 16, v15
	v_and_b32_e32 v19, 0xffff0000, v15
	v_add_f32_e32 v17, v17, v18
	v_add_f32_e32 v17, v17, v19
	ds_read_b64_tr_b16 v[0:1], v16 offset:4096
	ds_read_b64_tr_b16 v[2:3], v16 offset:4608
	ds_read_b64_tr_b16 v[4:5], v16 offset:5120
	ds_read_b64_tr_b16 v[6:7], v16 offset:5632
	ds_read_b64_tr_b16 v[8:9], v16 offset:6144
	ds_read_b64_tr_b16 v[10:11], v16 offset:6656
	ds_read_b64_tr_b16 v[12:13], v16 offset:7168
	ds_read_b64_tr_b16 v[14:15], v16 offset:7680
	s_waitcnt lgkmcnt(7)
	v_lshlrev_b32_e32 v18, 16, v0
	v_and_b32_e32 v19, 0xffff0000, v0
	v_add_f32_e32 v17, v17, v18
	v_add_f32_e32 v17, v17, v19
	v_lshlrev_b32_e32 v18, 16, v1
	v_and_b32_e32 v19, 0xffff0000, v1
	v_add_f32_e32 v17, v17, v18
	v_add_f32_e32 v17, v17, v19
	s_waitcnt lgkmcnt(6)
	v_lshlrev_b32_e32 v18, 16, v2
	v_and_b32_e32 v19, 0xffff0000, v2
	v_add_f32_e32 v17, v17, v18
	v_add_f32_e32 v17, v17, v19
	v_lshlrev_b32_e32 v18, 16, v3
	v_and_b32_e32 v19, 0xffff0000, v3
	v_add_f32_e32 v17, v17, v18
	v_add_f32_e32 v17, v17, v19
	s_waitcnt lgkmcnt(5)
	v_lshlrev_b32_e32 v18, 16, v4
	v_and_b32_e32 v19, 0xffff0000, v4
	v_add_f32_e32 v17, v17, v18
	v_add_f32_e32 v17, v17, v19
	v_lshlrev_b32_e32 v18, 16, v5
	v_and_b32_e32 v19, 0xffff0000, v5
	v_add_f32_e32 v17, v17, v18
	v_add_f32_e32 v17, v17, v19
	s_waitcnt lgkmcnt(4)
	v_lshlrev_b32_e32 v18, 16, v6
	v_and_b32_e32 v19, 0xffff0000, v6
	v_add_f32_e32 v17, v17, v18
	v_add_f32_e32 v17, v17, v19
	v_lshlrev_b32_e32 v18, 16, v7
	v_and_b32_e32 v19, 0xffff0000, v7
	v_add_f32_e32 v17, v17, v18
	v_add_f32_e32 v17, v17, v19
	s_waitcnt lgkmcnt(3)
	v_lshlrev_b32_e32 v18, 16, v8
	v_and_b32_e32 v19, 0xffff0000, v8
	v_add_f32_e32 v17, v17, v18
	v_add_f32_e32 v17, v17, v19
	v_lshlrev_b32_e32 v18, 16, v9
	v_and_b32_e32 v19, 0xffff0000, v9
	v_add_f32_e32 v17, v17, v18
	v_add_f32_e32 v17, v17, v19
	s_waitcnt lgkmcnt(2)
	v_lshlrev_b32_e32 v18, 16, v10
	v_and_b32_e32 v19, 0xffff0000, v10
	v_add_f32_e32 v17, v17, v18
	v_add_f32_e32 v17, v17, v19
	v_lshlrev_b32_e32 v18, 16, v11
	v_and_b32_e32 v19, 0xffff0000, v11
	v_add_f32_e32 v17, v17, v18
	v_add_f32_e32 v17, v17, v19
	s_waitcnt lgkmcnt(1)
	v_lshlrev_b32_e32 v18, 16, v12
	v_and_b32_e32 v19, 0xffff0000, v12
	v_add_f32_e32 v17, v17, v18
	v_add_f32_e32 v17, v17, v19
	v_lshlrev_b32_e32 v18, 16, v13
	v_and_b32_e32 v19, 0xffff0000, v13
	v_add_f32_e32 v17, v17, v18
	v_add_f32_e32 v17, v17, v19
	s_waitcnt lgkmcnt(0)
	v_lshlrev_b32_e32 v18, 16, v14
	v_and_b32_e32 v19, 0xffff0000, v14
	v_add_f32_e32 v17, v17, v18
	v_add_f32_e32 v17, v17, v19
	v_lshlrev_b32_e32 v18, 16, v15
	v_and_b32_e32 v19, 0xffff0000, v15
	v_add_f32_e32 v17, v17, v18
	v_add_f32_e32 v17, v17, v19
	ds_read_b64_tr_b16 v[0:1], v16 offset:8192
	ds_read_b64_tr_b16 v[2:3], v16 offset:8704
	ds_read_b64_tr_b16 v[4:5], v16 offset:9216
	ds_read_b64_tr_b16 v[6:7], v16 offset:9728
	ds_read_b64_tr_b16 v[8:9], v16 offset:10240
	ds_read_b64_tr_b16 v[10:11], v16 offset:10752
	ds_read_b64_tr_b16 v[12:13], v16 offset:11264
	ds_read_b64_tr_b16 v[14:15], v16 offset:11776
	s_waitcnt lgkmcnt(7)
	v_lshlrev_b32_e32 v18, 16, v0
	v_and_b32_e32 v19, 0xffff0000, v0
	v_add_f32_e32 v17, v17, v18
	v_add_f32_e32 v17, v17, v19
	v_lshlrev_b32_e32 v18, 16, v1
	v_and_b32_e32 v19, 0xffff0000, v1
	v_add_f32_e32 v17, v17, v18
	v_add_f32_e32 v17, v17, v19
	s_waitcnt lgkmcnt(6)
	v_lshlrev_b32_e32 v18, 16, v2
	v_and_b32_e32 v19, 0xffff0000, v2
	v_add_f32_e32 v17, v17, v18
	v_add_f32_e32 v17, v17, v19
	v_lshlrev_b32_e32 v18, 16, v3
	v_and_b32_e32 v19, 0xffff0000, v3
	v_add_f32_e32 v17, v17, v18
	v_add_f32_e32 v17, v17, v19
	s_waitcnt lgkmcnt(5)
	v_lshlrev_b32_e32 v18, 16, v4
	v_and_b32_e32 v19, 0xffff0000, v4
	v_add_f32_e32 v17, v17, v18
	v_add_f32_e32 v17, v17, v19
	v_lshlrev_b32_e32 v18, 16, v5
	v_and_b32_e32 v19, 0xffff0000, v5
	v_add_f32_e32 v17, v17, v18
	v_add_f32_e32 v17, v17, v19
	s_waitcnt lgkmcnt(4)
	v_lshlrev_b32_e32 v18, 16, v6
	v_and_b32_e32 v19, 0xffff0000, v6
	v_add_f32_e32 v17, v17, v18
	v_add_f32_e32 v17, v17, v19
	v_lshlrev_b32_e32 v18, 16, v7
	v_and_b32_e32 v19, 0xffff0000, v7
	v_add_f32_e32 v17, v17, v18
	v_add_f32_e32 v17, v17, v19
	s_waitcnt lgkmcnt(3)
	v_lshlrev_b32_e32 v18, 16, v8
	v_and_b32_e32 v19, 0xffff0000, v8
	v_add_f32_e32 v17, v17, v18
	v_add_f32_e32 v17, v17, v19
	v_lshlrev_b32_e32 v18, 16, v9
	v_and_b32_e32 v19, 0xffff0000, v9
	v_add_f32_e32 v17, v17, v18
	v_add_f32_e32 v17, v17, v19
	s_waitcnt lgkmcnt(2)
	v_lshlrev_b32_e32 v18, 16, v10
	v_and_b32_e32 v19, 0xffff0000, v10
	v_add_f32_e32 v17, v17, v18
	v_add_f32_e32 v17, v17, v19
	v_lshlrev_b32_e32 v18, 16, v11
	v_and_b32_e32 v19, 0xffff0000, v11
	v_add_f32_e32 v17, v17, v18
	v_add_f32_e32 v17, v17, v19
	s_waitcnt lgkmcnt(1)
	v_lshlrev_b32_e32 v18, 16, v12
	v_and_b32_e32 v19, 0xffff0000, v12
	v_add_f32_e32 v17, v17, v18
	v_add_f32_e32 v17, v17, v19
	v_lshlrev_b32_e32 v18, 16, v13
	v_and_b32_e32 v19, 0xffff0000, v13
	v_add_f32_e32 v17, v17, v18
	v_add_f32_e32 v17, v17, v19
	s_waitcnt lgkmcnt(0)
	v_lshlrev_b32_e32 v18, 16, v14
	v_and_b32_e32 v19, 0xffff0000, v14
	v_add_f32_e32 v17, v17, v18
	v_add_f32_e32 v17, v17, v19
	v_lshlrev_b32_e32 v18, 16, v15
	v_and_b32_e32 v19, 0xffff0000, v15
	v_add_f32_e32 v17, v17, v18
	v_add_f32_e32 v17, v17, v19
	ds_read_b64_tr_b16 v[0:1], v16 offset:12288
	ds_read_b64_tr_b16 v[2:3], v16 offset:12800
	ds_read_b64_tr_b16 v[4:5], v16 offset:13312
	ds_read_b64_tr_b16 v[6:7], v16 offset:13824
	ds_read_b64_tr_b16 v[8:9], v16 offset:14336
	ds_read_b64_tr_b16 v[10:11], v16 offset:14848
	ds_read_b64_tr_b16 v[12:13], v16 offset:15360
	ds_read_b64_tr_b16 v[14:15], v16 offset:15872
	s_waitcnt lgkmcnt(7)
	v_lshlrev_b32_e32 v18, 16, v0
	v_and_b32_e32 v19, 0xffff0000, v0
	v_add_f32_e32 v17, v17, v18
	v_add_f32_e32 v17, v17, v19
	v_lshlrev_b32_e32 v18, 16, v1
	v_and_b32_e32 v19, 0xffff0000, v1
	v_add_f32_e32 v17, v17, v18
	v_add_f32_e32 v17, v17, v19
	s_waitcnt lgkmcnt(6)
	v_lshlrev_b32_e32 v18, 16, v2
	v_and_b32_e32 v19, 0xffff0000, v2
	v_add_f32_e32 v17, v17, v18
	v_add_f32_e32 v17, v17, v19
	v_lshlrev_b32_e32 v18, 16, v3
	v_and_b32_e32 v19, 0xffff0000, v3
	v_add_f32_e32 v17, v17, v18
	v_add_f32_e32 v17, v17, v19
	s_waitcnt lgkmcnt(5)
	v_lshlrev_b32_e32 v18, 16, v4
	v_and_b32_e32 v19, 0xffff0000, v4
	v_add_f32_e32 v17, v17, v18
	v_add_f32_e32 v17, v17, v19
	v_lshlrev_b32_e32 v18, 16, v5
	v_and_b32_e32 v19, 0xffff0000, v5
	v_add_f32_e32 v17, v17, v18
	v_add_f32_e32 v17, v17, v19
	s_waitcnt lgkmcnt(4)
	v_lshlrev_b32_e32 v18, 16, v6
	v_and_b32_e32 v19, 0xffff0000, v6
	v_add_f32_e32 v17, v17, v18
	v_add_f32_e32 v17, v17, v19
	v_lshlrev_b32_e32 v18, 16, v7
	v_and_b32_e32 v19, 0xffff0000, v7
	v_add_f32_e32 v17, v17, v18
	v_add_f32_e32 v17, v17, v19
	s_waitcnt lgkmcnt(3)
	v_lshlrev_b32_e32 v18, 16, v8
	v_and_b32_e32 v19, 0xffff0000, v8
	v_add_f32_e32 v17, v17, v18
	v_add_f32_e32 v17, v17, v19
	v_lshlrev_b32_e32 v18, 16, v9
	v_and_b32_e32 v19, 0xffff0000, v9
	v_add_f32_e32 v17, v17, v18
	v_add_f32_e32 v17, v17, v19
	s_waitcnt lgkmcnt(2)
	v_lshlrev_b32_e32 v18, 16, v10
	v_and_b32_e32 v19, 0xffff0000, v10
	v_add_f32_e32 v17, v17, v18
	v_add_f32_e32 v17, v17, v19
	v_lshlrev_b32_e32 v18, 16, v11
	v_and_b32_e32 v19, 0xffff0000, v11
	v_add_f32_e32 v17, v17, v18
	v_add_f32_e32 v17, v17, v19
	s_waitcnt lgkmcnt(1)
	v_lshlrev_b32_e32 v18, 16, v12
	v_and_b32_e32 v19, 0xffff0000, v12
	v_add_f32_e32 v17, v17, v18
	v_add_f32_e32 v17, v17, v19
	v_lshlrev_b32_e32 v18, 16, v13
	v_and_b32_e32 v19, 0xffff0000, v13
	v_add_f32_e32 v17, v17, v18
	v_add_f32_e32 v17, v17, v19
	s_waitcnt lgkmcnt(0)
	v_lshlrev_b32_e32 v18, 16, v14
	v_and_b32_e32 v19, 0xffff0000, v14
	v_add_f32_e32 v17, v17, v18
	v_add_f32_e32 v17, v17, v19
	v_lshlrev_b32_e32 v18, 16, v15
	v_and_b32_e32 v19, 0xffff0000, v15
	v_add_f32_e32 v17, v17, v18
	v_add_f32_e32 v17, v17, v19
	v_lshlrev_b32_e32 v2, 1, v210
	v_mov_b32_e32 v3, v17
	v_add3_u32 v0, s36, 4, v2
	v_lshl_or_b32 v4, v0, 3, s37
	v_mov_b32_e32 v0, s0
	v_mov_b32_e32 v1, s35
	v_cndmask_b32_e32 v0, v0, v1, vcc
	v_ashrrev_i32_e32 v1, 31, v0
	v_mad_i64_i32 v[0:1], s[0:1], v4, s90, v[0:1]
	v_lshlrev_b64 v[4:5], 8, v[0:1]
	v_lshl_add_u64 v[4:5], s[22:23], 0, v[4:5]
	v_lshlrev_b32_e32 v160, 2, v208
	v_lshl_add_u64 v[4:5], v[4:5], 0, v[160:161]
	v_cmp_eq_u32_e32 vcc, 0, v208
	global_store_dword v[4:5], v3, off
	s_and_b64 exec, exec, vcc
	s_cbranch_execz .LBB0_958
	v_lshl_add_u32 v2, v2, 2, s33
	ds_read_b64 v[2:3], v2 offset:53248
	v_lshl_add_u64 v[0:1], v[0:1], 3, s[24:25]
	s_waitcnt lgkmcnt(0)
	v_add_f32_e32 v4, v2, v3
	v_mov_b32_e32 v5, v2
	global_store_dwordx2 v[0:1], v[4:5], off
	s_branch .LBB0_958
